# baseline (speedup 1.0000x reference)
.LBB0_749:
.LBB0_750:
	ds_read_b128 v[124:127], v227 offset:36864
	ds_read_b128 v[202:205], v227 offset:41472
	ds_read_b128 v[230:233], v227 offset:46080
	ds_read_b128 v[234:237], v227 offset:50688
	s_min_u32 s2, s1, 0xfb
	s_min_u32 s3, s1, 0xfd
	s_nop 1
	v_exp_f32_e32 v229, v128
	v_exp_f32_e32 v252, v144
	v_exp_f32_e32 v14, v129
	v_exp_f32_e32 v0, v145
	s_waitcnt lgkmcnt(3)
	v_mfma_f32_32x32x16_bf16 v[64:79], v[124:127], v[120:123], v[64:79]
	v_add_f32_e32 v15, v229, v252
	v_exp_f32_e32 v213, v130
	v_pk_add_f32 v[128:129], v[14:15], v[0:1]
	v_exp_f32_e32 v214, v146
	v_exp_f32_e32 v206, v131
	ds_read_b128 v[124:127], v227 offset:36896
	ds_read_b128 v[238:241], v227 offset:41504
	ds_read_b128 v[242:245], v227 offset:46112
	ds_read_b128 v[246:249], v227 offset:50720
	s_waitcnt lgkmcnt(6)
	v_mfma_f32_32x32x16_bf16 v[48:63], v[202:205], v[120:123], v[48:63]
	v_add_f32_e64 v202, v128, v128
	v_add_f32_e64 v203, v128, v129
	v_exp_f32_e32 v202, v147
	v_add_f32_e32 v207, v213, v214
	s_lshl_b32 s2, s2, 17
	v_max_i32_e32 v15, v14, v0
	s_add_i32 s42, s2, 0x80000
	s_lshl_b32 s2, s3, 14
	s_waitcnt lgkmcnt(5)
	v_mfma_f32_32x32x16_bf16 v[32:47], v[230:233], v[120:123], v[32:47]
	v_max3_i32 v15, v229, v252, v15
	v_max_i32_e32 v128, v213, v214
	v_lshl_add_u64 v[250:251], v[192:193], 0, s[42:43]
	v_lshl_add_u64 v[180:181], v[196:197], 0, s[42:43]
	s_add_i32 s42, s2, 0x8000
	v_lshl_add_u64 v[182:183], v[194:195], 0, s[42:43]
	v_lshl_add_u64 v[184:185], v[198:199], 0, s[42:43]
	s_waitcnt lgkmcnt(4)
	v_mfma_f32_32x32x16_bf16 v[16:31], v[234:237], v[120:123], v[16:31]
	v_add_f32_e64 v120, v206, v202
	v_add_f32_e64 v121, v207, v203
	v_add_f32_e64 v204, v120, v120
	v_add_f32_e64 v205, v120, v121
	v_max_i32_e32 v120, v206, v202
	v_max3_i32 v15, v15, v128, v120
	ds_read_b128 v[120:123], v227 offset:36928
	ds_read_b128 v[230:233], v227 offset:41536
	ds_read_b128 v[234:237], v227 offset:46144
	ds_read_b128 v[176:179], v227 offset:50752
	s_waitcnt vmcnt(3)
	ds_write_b128 v221, v[10:13] offset:18432
	s_waitcnt vmcnt(2)
	ds_write_b128 v221, v[112:115] offset:23040
	s_waitcnt vmcnt(1)
	ds_write_b128 v222, v[168:171] offset:55296
	s_waitcnt vmcnt(0)
	ds_write_b128 v222, v[172:175] offset:64512
	global_load_dwordx4 v[128:131], v[250:251], off
	global_load_dwordx4 v[144:147], v[180:181], off
	global_load_dwordx4 v[168:171], v[182:183], off
	global_load_dwordx4 v[172:175], v[184:185], off
	v_exp_f32_e32 v203, v132
	v_exp_f32_e32 v207, v148
	v_exp_f32_e32 v180, v133
	v_exp_f32_e32 v204, v149
	s_waitcnt lgkmcnt(11)
	v_mfma_f32_32x32x16_bf16 v[64:79], v[124:127], v[116:119], v[64:79]
	v_add_f32_e32 v181, v203, v207
	v_max_i32_e32 v12, v203, v207
	v_add_f32_e64 v10, v180, v204
	v_add_f32_e64 v11, v181, v205
	v_exp_f32_e32 v181, v134
	v_exp_f32_e32 v205, v150
	v_pk_add_f32 v[182:183], v[10:11], v[10:11] op_sel_hi:[0,1]
	v_max_i32_e32 v10, v180, v204
	s_waitcnt lgkmcnt(10)
	v_mfma_f32_32x32x16_bf16 v[48:63], v[238:241], v[116:119], v[48:63]
	v_max3_i32 v15, v15, v12, v10
	v_max_i32_e32 v126, v181, v205
	v_add_f32_e32 v185, v181, v205
	s_waitcnt lgkmcnt(9)
	v_mfma_f32_32x32x16_bf16 v[32:47], v[242:245], v[116:119], v[32:47]
	s_waitcnt lgkmcnt(8)
	v_mfma_f32_32x32x16_bf16 v[16:31], v[246:249], v[116:119], v[16:31]
	v_exp_f32_e32 v184, v135
	v_exp_f32_e32 v182, v151
	s_waitcnt lgkmcnt(7)
	v_mfma_f32_32x32x16_bf16 v[64:79], v[120:123], v[6:9], v[64:79]
	ds_read_b128 v[10:13], v227 offset:36960
	ds_read_b128 v[112:115], v227 offset:41568
	ds_read_b128 v[116:119], v227 offset:46176
	ds_read_b128 v[120:123], v227 offset:50784
	v_add_f32_e64 v124, v184, v182
	v_add_f32_e64 v125, v185, v183
	v_exp_f32_e32 v183, v136
	v_exp_f32_e32 v185, v152
	s_waitcnt lgkmcnt(10)
	v_mfma_f32_32x32x16_bf16 v[48:63], v[230:233], v[6:9], v[48:63]
	v_add_f32_e64 v230, v124, v124
	v_add_f32_e64 v231, v124, v125
	v_exp_f32_e32 v232, v137
	v_exp_f32_e32 v230, v153
	v_max_i32_e32 v124, v184, v182
	v_add_f32_e32 v233, v183, v185
	v_max3_i32 v15, v15, v126, v124
	v_pk_add_f32 v[124:125], v[232:233], v[230:231]
	s_waitcnt lgkmcnt(9)
	v_mfma_f32_32x32x16_bf16 v[32:47], v[234:237], v[6:9], v[32:47]
	v_max_i32_e32 v126, v183, v185
	v_add_f32_e64 v234, v124, v124
	v_add_f32_e64 v235, v124, v125
	v_max_i32_e32 v124, v232, v230
	v_max3_i32 v15, v15, v126, v124
	s_waitcnt lgkmcnt(8)
	v_mfma_f32_32x32x16_bf16 v[16:31], v[176:179], v[6:9], v[16:31]
	v_exp_f32_e32 v231, v138
	v_exp_f32_e32 v233, v154
	s_waitcnt lgkmcnt(3)
	v_mfma_f32_32x32x16_bf16 v[64:79], v[10:13], v[2:5], v[64:79]
	v_exp_f32_e32 v236, v139
	v_exp_f32_e32 v234, v155
	ds_read_b128 v[6:9], v223
	ds_read_b128 v[10:13], v223 offset:32
	ds_read_b128 v[132:135], v223 offset:4608
	ds_read_b128 v[148:151], v223 offset:4640
	v_add_f32_e32 v237, v231, v233
	v_exp_f32_e32 v156, v156
	s_waitcnt lgkmcnt(6)
	v_mfma_f32_32x32x16_bf16 v[48:63], v[112:115], v[2:5], v[48:63]
	v_add_f32_e64 v112, v236, v234
	v_add_f32_e64 v113, v237, v235
	v_exp_f32_e32 v235, v140
	v_max_i32_e32 v114, v231, v233
	v_pk_add_f32 v[238:239], v[112:113], v[112:113] op_sel_hi:[0,1]
	v_max_i32_e32 v112, v236, v234
	v_max3_i32 v15, v15, v114, v112
	v_add_f32_e32 v241, v235, v156
	s_waitcnt lgkmcnt(5)
	v_mfma_f32_32x32x16_bf16 v[32:47], v[116:119], v[2:5], v[32:47]
	v_max_i32_e32 v237, v235, v156
	s_waitcnt lgkmcnt(4)
	v_mfma_f32_32x32x16_bf16 v[16:31], v[120:123], v[2:5], v[16:31]
	s_waitcnt lgkmcnt(3)
	v_mfma_f32_32x32x16_bf16 v[112:127], v[6:9], v[160:163], v[96:111]
	v_exp_f32_e32 v240, v141
	v_exp_f32_e32 v238, v157
	v_exp_f32_e32 v158, v158
	ds_read_b128 v[2:5], v223 offset:64
	ds_read_b128 v[136:139], v223 offset:96
	ds_read_b128 v[6:9], v223 offset:4672
	ds_read_b128 v[152:155], v223 offset:4704
	v_pk_add_f32 v[140:141], v[240:241], v[238:239]
	s_nop 0
	v_pk_add_f32 v[140:141], v[140:141], v[140:141] op_sel_hi:[0,1]
	s_waitcnt lgkmcnt(5)
	v_mfma_f32_32x32x16_bf16 v[80:95], v[132:135], v[160:163], v[96:111]
	v_exp_f32_e32 v239, v142
	v_exp_f32_e32 v142, v143
	v_exp_f32_e32 v140, v159
	ds_read_b128 v[132:135], v224
	ds_read_b128 v[176:179], v224 offset:1024
	v_add_f32_e32 v143, v239, v158
	v_max_i32_e32 v157, v240, v238
	v_mfma_f32_32x32x16_bf16 v[112:127], v[10:13], v[164:167], v[112:127]
	v_add_f32_e64 v10, v142, v140
	v_add_f32_e64 v11, v143, v141
	v_max3_i32 v12, v15, v237, v157
	v_max_i32_e32 v13, v239, v158
	v_add_f32_e32 v141, v10, v11
	v_max_i32_e32 v10, v142, v140
	v_max3_i32 v15, v12, v13, v10
	s_waitcnt lgkmcnt(6)
	v_mfma_f32_32x32x16_bf16 v[80:95], v[148:151], v[164:167], v[80:95]
	s_waitcnt lgkmcnt(1)
	v_mfma_f32_32x32x16_bf16 v[112:127], v[2:5], v[132:135], v[112:127]
	v_cvt_pk_bf16_f32 v10, v229, v14
	v_cvt_pk_bf16_f32 v11, v213, v206
	v_cvt_pk_bf16_f32 v12, v203, v180
	v_cvt_pk_bf16_f32 v13, v181, v184
	v_cvt_pk_bf16_f32 v2, v252, v0
	v_cvt_pk_bf16_f32 v3, v214, v202
	v_cvt_pk_bf16_f32 v4, v207, v204
	v_mfma_f32_32x32x16_bf16 v[80:95], v[6:9], v[132:135], v[80:95]
	v_cvt_pk_bf16_f32 v6, v183, v232
	v_cvt_pk_bf16_f32 v7, v231, v236
	v_cvt_pk_bf16_f32 v8, v235, v240
	v_cvt_pk_bf16_f32 v9, v239, v142
	v_cvt_pk_bf16_f32 v5, v205, v182
	v_cvt_pk_bf16_f32 v132, v185, v230
	v_cvt_pk_bf16_f32 v133, v233, v234
	s_waitcnt lgkmcnt(0)
	v_mfma_f32_32x32x16_bf16 v[112:127], v[136:139], v[176:179], v[112:127]
	v_cvt_pk_bf16_f32 v134, v156, v238
	v_cvt_pk_bf16_f32 v135, v158, v140
	v_mfma_f32_32x32x16_bf16 v[80:95], v[152:155], v[176:179], v[80:95]
	v_add_f32_e32 v204, v228, v141
	v_cmp_lt_i32_e32 vcc, s64, v15
	s_barrier
	s_cbranch_vccz .LBB0_746
	v_max_i32_e32 v0, 0, v15
	ds_bpermute_b32 v14, v189, v0
	v_and_b32_e32 v15, 0xffff0000, v10
	s_waitcnt lgkmcnt(0)
	v_max_i32_e32 v0, v0, v14
	v_log_f32_e32 v0, v0
	v_lshlrev_b32_e32 v14, 16, v10
	v_max_f32_e32 v97, 0, v0
	v_exp_f32_e64 v0, -v97
	v_add_f32_e32 v226, v226, v97
	v_xor_b32_e32 v96, 0x80000000, v226
	v_sub_f32_e32 v95, v95, v97
	v_pk_mul_f32 v[14:15], v[0:1], v[14:15] op_sel_hi:[0,1]
	v_cvt_pk_bf16_f32 v10, v14, v15
	v_lshlrev_b32_e32 v14, 16, v11
	v_and_b32_e32 v15, 0xffff0000, v11
	v_pk_mul_f32 v[14:15], v[0:1], v[14:15] op_sel_hi:[0,1]
	v_cvt_pk_bf16_f32 v11, v14, v15
	v_lshlrev_b32_e32 v14, 16, v12
	v_and_b32_e32 v15, 0xffff0000, v12
	v_pk_mul_f32 v[14:15], v[0:1], v[14:15] op_sel_hi:[0,1]
	v_cvt_pk_bf16_f32 v12, v14, v15
	v_lshlrev_b32_e32 v14, 16, v13
	v_and_b32_e32 v15, 0xffff0000, v13
	v_pk_mul_f32 v[14:15], v[0:1], v[14:15] op_sel_hi:[0,1]
	v_cvt_pk_bf16_f32 v13, v14, v15
	v_lshlrev_b32_e32 v14, 16, v6
	v_and_b32_e32 v15, 0xffff0000, v6
	v_pk_mul_f32 v[14:15], v[0:1], v[14:15] op_sel_hi:[0,1]
	v_cvt_pk_bf16_f32 v6, v14, v15
	v_lshlrev_b32_e32 v14, 16, v7
	v_and_b32_e32 v15, 0xffff0000, v7
	v_pk_mul_f32 v[14:15], v[0:1], v[14:15] op_sel_hi:[0,1]
	v_cvt_pk_bf16_f32 v7, v14, v15
	v_lshlrev_b32_e32 v14, 16, v8
	v_and_b32_e32 v15, 0xffff0000, v8
	v_pk_mul_f32 v[14:15], v[0:1], v[14:15] op_sel_hi:[0,1]
	v_cvt_pk_bf16_f32 v8, v14, v15
	v_lshlrev_b32_e32 v14, 16, v9
	v_and_b32_e32 v15, 0xffff0000, v9
	v_pk_mul_f32 v[14:15], v[0:1], v[14:15] op_sel_hi:[0,1]
	v_cvt_pk_bf16_f32 v9, v14, v15
	v_lshlrev_b32_e32 v14, 16, v2
	v_and_b32_e32 v15, 0xffff0000, v2
	v_pk_mul_f32 v[14:15], v[0:1], v[14:15] op_sel_hi:[0,1]
	v_cvt_pk_bf16_f32 v2, v14, v15
	v_lshlrev_b32_e32 v14, 16, v3
	v_and_b32_e32 v15, 0xffff0000, v3
	v_pk_mul_f32 v[14:15], v[0:1], v[14:15] op_sel_hi:[0,1]
	v_cvt_pk_bf16_f32 v3, v14, v15
	v_lshlrev_b32_e32 v14, 16, v4
	v_and_b32_e32 v15, 0xffff0000, v4
	v_pk_mul_f32 v[14:15], v[0:1], v[14:15] op_sel_hi:[0,1]
	v_cvt_pk_bf16_f32 v4, v14, v15
	v_lshlrev_b32_e32 v14, 16, v5
	v_and_b32_e32 v15, 0xffff0000, v5
	v_pk_mul_f32 v[14:15], v[0:1], v[14:15] op_sel_hi:[0,1]
	v_cvt_pk_bf16_f32 v5, v14, v15
	v_lshlrev_b32_e32 v14, 16, v132
	v_and_b32_e32 v15, 0xffff0000, v132
	v_pk_mul_f32 v[14:15], v[0:1], v[14:15] op_sel_hi:[0,1]
	v_cvt_pk_bf16_f32 v132, v14, v15
	v_lshlrev_b32_e32 v14, 16, v133
	v_and_b32_e32 v15, 0xffff0000, v133
	v_pk_mul_f32 v[14:15], v[0:1], v[14:15] op_sel_hi:[0,1]
	v_cvt_pk_bf16_f32 v133, v14, v15
	v_lshlrev_b32_e32 v14, 16, v134
	v_and_b32_e32 v15, 0xffff0000, v134
	v_pk_mul_f32 v[14:15], v[0:1], v[14:15] op_sel_hi:[0,1]
	v_cvt_pk_bf16_f32 v134, v14, v15
	v_lshlrev_b32_e32 v14, 16, v135
	v_and_b32_e32 v15, 0xffff0000, v135
	v_pk_mul_f32 v[14:15], v[0:1], v[14:15] op_sel_hi:[0,1]
	v_pk_mul_f32 v[78:79], v[78:79], v[0:1] op_sel_hi:[1,0]
	v_pk_mul_f32 v[76:77], v[76:77], v[0:1] op_sel_hi:[1,0]
	v_pk_mul_f32 v[74:75], v[74:75], v[0:1] op_sel_hi:[1,0]
	v_pk_mul_f32 v[72:73], v[72:73], v[0:1] op_sel_hi:[1,0]
	v_pk_mul_f32 v[70:71], v[70:71], v[0:1] op_sel_hi:[1,0]
	v_pk_mul_f32 v[68:69], v[68:69], v[0:1] op_sel_hi:[1,0]
	v_pk_mul_f32 v[66:67], v[66:67], v[0:1] op_sel_hi:[1,0]
	v_pk_mul_f32 v[64:65], v[64:65], v[0:1] op_sel_hi:[1,0]
	v_pk_mul_f32 v[62:63], v[62:63], v[0:1] op_sel_hi:[1,0]
	v_pk_mul_f32 v[60:61], v[60:61], v[0:1] op_sel_hi:[1,0]
	v_pk_mul_f32 v[58:59], v[58:59], v[0:1] op_sel_hi:[1,0]
	v_pk_mul_f32 v[56:57], v[56:57], v[0:1] op_sel_hi:[1,0]
	v_pk_mul_f32 v[54:55], v[54:55], v[0:1] op_sel_hi:[1,0]
	v_pk_mul_f32 v[52:53], v[52:53], v[0:1] op_sel_hi:[1,0]
	v_pk_mul_f32 v[50:51], v[50:51], v[0:1] op_sel_hi:[1,0]
	v_pk_mul_f32 v[48:49], v[48:49], v[0:1] op_sel_hi:[1,0]
	v_pk_mul_f32 v[46:47], v[46:47], v[0:1] op_sel_hi:[1,0]
	v_pk_mul_f32 v[44:45], v[44:45], v[0:1] op_sel_hi:[1,0]
	v_pk_mul_f32 v[42:43], v[42:43], v[0:1] op_sel_hi:[1,0]
	v_pk_mul_f32 v[40:41], v[40:41], v[0:1] op_sel_hi:[1,0]
	v_pk_mul_f32 v[38:39], v[38:39], v[0:1] op_sel_hi:[1,0]
	v_pk_mul_f32 v[36:37], v[36:37], v[0:1] op_sel_hi:[1,0]
	v_pk_mul_f32 v[34:35], v[34:35], v[0:1] op_sel_hi:[1,0]
	v_pk_mul_f32 v[32:33], v[32:33], v[0:1] op_sel_hi:[1,0]
	v_pk_mul_f32 v[30:31], v[30:31], v[0:1] op_sel_hi:[1,0]
	v_pk_mul_f32 v[28:29], v[28:29], v[0:1] op_sel_hi:[1,0]
	v_pk_mul_f32 v[26:27], v[26:27], v[0:1] op_sel_hi:[1,0]
	v_pk_mul_f32 v[24:25], v[24:25], v[0:1] op_sel_hi:[1,0]
	v_pk_mul_f32 v[22:23], v[22:23], v[0:1] op_sel_hi:[1,0]
	v_pk_mul_f32 v[20:21], v[20:21], v[0:1] op_sel_hi:[1,0]
	v_pk_mul_f32 v[18:19], v[18:19], v[0:1] op_sel_hi:[1,0]
	v_pk_mul_f32 v[16:17], v[16:17], v[0:1] op_sel_hi:[1,0]
	v_sub_f32_e32 v94, v94, v97
	v_sub_f32_e32 v93, v93, v97
	v_sub_f32_e32 v92, v92, v97
	v_sub_f32_e32 v91, v91, v97
	v_sub_f32_e32 v90, v90, v97
	v_sub_f32_e32 v89, v89, v97
	v_sub_f32_e32 v88, v88, v97
	v_sub_f32_e32 v87, v87, v97
	v_sub_f32_e32 v86, v86, v97
	v_sub_f32_e32 v85, v85, v97
	v_sub_f32_e32 v84, v84, v97
	v_sub_f32_e32 v83, v83, v97
	v_sub_f32_e32 v82, v82, v97
	v_sub_f32_e32 v81, v81, v97
	v_sub_f32_e32 v80, v80, v97
	v_cvt_pk_bf16_f32 v135, v14, v15
	v_sub_f32_e32 v127, v127, v97
	v_sub_f32_e32 v126, v126, v97
	v_sub_f32_e32 v125, v125, v97
	v_sub_f32_e32 v124, v124, v97
	v_sub_f32_e32 v123, v123, v97
	v_sub_f32_e32 v122, v122, v97
	v_sub_f32_e32 v121, v121, v97
	v_sub_f32_e32 v120, v120, v97
	v_sub_f32_e32 v119, v119, v97
	v_sub_f32_e32 v118, v118, v97
	v_sub_f32_e32 v117, v117, v97
	v_sub_f32_e32 v116, v116, v97
	v_sub_f32_e32 v115, v115, v97
	v_sub_f32_e32 v114, v114, v97
	v_sub_f32_e32 v113, v113, v97
	v_sub_f32_e32 v112, v112, v97
	v_mul_f32_e32 v204, v204, v0
	v_mov_b32_e32 v97, v96
	v_mov_b32_e32 v98, v96
	v_mov_b32_e32 v99, v96
	v_mov_b32_e32 v100, v96
	v_mov_b32_e32 v101, v96
	v_mov_b32_e32 v102, v96
	v_mov_b32_e32 v103, v96
	v_mov_b32_e32 v104, v96
	v_mov_b32_e32 v105, v96
	v_mov_b32_e32 v106, v96
	v_mov_b32_e32 v107, v96
	v_mov_b32_e32 v108, v96
	v_mov_b32_e32 v109, v96
	v_mov_b32_e32 v110, v96
	v_mov_b32_e32 v111, v96
	s_branch .LBB0_746
